# UP pass sharing across XCDs: owner writes back L2 before publishing, 36 helper workgroups on all XCDs
# speedup vs baseline: 1.1108x; 1.0359x over previous
; DI int otid() { int t = threadIdx.x; asm volatile("" : "+v"(t)); return t; }
; template <int MODE, int MT> DI void norm_rows(const float* src, const float* src2, float* x, int d2, bf16_t* xb, const float* __restrict__ g) {
;     const int tid_ = otid(), wave = tid_ >> 6, lane = tid_ & 63;
;     for (int rb = 0; rb < MT; ++rb) {
;         f32x4 v[4][4]; float ss[4];
; #pragma unroll
;         for (int q = 0; q < 4; ++q) {
;             const int row = wave * (MT * 4) + rb * 4 + q, grow = row + (row >= 64 ? d2 : 0);
;             const float* s = x + (size_t)grow * DM;
;             if (MODE == 0) { s = src + (size_t)row * DM; if (MT == 3 && row >= 64) s = src2 + (size_t)(row - 64) * DM; }
;             ss[q] = 0.f;
; #pragma unroll
;             for (int i = 0; i < 4; ++i) { v[q][i] = *(const f32x4*)(s + i * 256 + lane * 4); ss[q] += v[q][i][0] * v[q][i][0] + v[q][i][1] * v[q][i][1] + v[q][i][2] * v[q][i][2] + v[q][i][3] * v[q][i][3]; }
;         }
.LBB0_457:
	v_mov_b32_e32 v2, v176
	s_waitcnt lgkmcnt(0)
	s_barrier
	v_mov_b32_e32 v3, v1
	v_ashrrev_i32_e32 v94, 6, v2
	v_lshlrev_b32_e32 v2, 2, v2
	v_and_b32_e32 v4, 0xfc, v2
	v_lshlrev_b32_e32 v2, 2, v4
	v_lshl_add_u64 v[68:69], s[0:1], 0, v[2:3]
	v_lshlrev_b32_e32 v2, 1, v4
	v_cmp_lt_i32_e32 vcc, 5, v94
	v_mov_b32_e32 v95, s24
	v_mul_lo_u32 v0, v94, 12
	v_lshl_add_u64 v[66:67], s[34:35], 0, v[2:3]
	v_cndmask_b32_e32 v2, 0, v95, vcc
	v_add_u32_e32 v92, v2, v0
	v_ashrrev_i32_e32 v93, 31, v92
	v_lshlrev_b64 v[2:3], 12, v[92:93]
	v_lshl_add_u64 v[2:3], v[68:69], 0, v[2:3]
	global_load_dwordx4 v[18:21], v[2:3], off
	global_load_dwordx4 v[10:13], v[2:3], off offset:1024
	global_load_dwordx4 v[38:41], v[2:3], off offset:2048
	global_load_dwordx4 v[30:33], v[2:3], off offset:3072
	v_add_u32_e32 v74, 1, v92
	v_ashrrev_i32_e32 v75, 31, v74
	s_mov_b32 s0, 0x358637bd
	s_mov_b32 s4, 0x3a800000
	s_mov_b32 s3, 0x800000
	v_lshlrev_b64 v[92:93], 11, v[92:93]
	v_lshl_add_u64 v[92:93], v[66:67], 0, v[92:93]
	s_mov_b32 s2, 0
	s_mov_b32 s31, 0
	s_waitcnt vmcnt(3)
	v_mov_b32_e32 v6, v19
	s_waitcnt vmcnt(2)
	v_mov_b32_e32 v7, v11
	v_mov_b32_e32 v4, v18
	v_mov_b32_e32 v5, v10
	v_pk_mul_f32 v[6:7], v[6:7], v[6:7]
	s_waitcnt vmcnt(1)
	v_mov_b32_e32 v2, v38
	v_pk_fma_f32 v[4:5], v[4:5], v[4:5], v[6:7]
	v_mov_b32_e32 v6, v20
	v_mov_b32_e32 v7, v12
	v_pk_fma_f32 v[4:5], v[6:7], v[6:7], v[4:5]
	v_mov_b32_e32 v6, v21
	v_mov_b32_e32 v7, v13
	v_pk_fma_f32 v[70:71], v[6:7], v[6:7], v[4:5]
	v_mov_b32_e32 v4, v39
	s_waitcnt vmcnt(0)
	v_mov_b32_e32 v5, v31
	v_mov_b32_e32 v3, v30
	v_pk_mul_f32 v[4:5], v[4:5], v[4:5]
	s_nop 0
	v_pk_fma_f32 v[2:3], v[2:3], v[2:3], v[4:5]
	v_mov_b32_e32 v4, v40
	v_mov_b32_e32 v5, v32
	v_pk_fma_f32 v[2:3], v[4:5], v[4:5], v[2:3]
	v_mov_b32_e32 v4, v41
	v_mov_b32_e32 v5, v33
	v_pk_fma_f32 v[82:83], v[4:5], v[4:5], v[2:3]
	v_lshlrev_b64 v[2:3], 12, v[74:75]
	v_lshl_add_u64 v[2:3], v[68:69], 0, v[2:3]
	global_load_dwordx4 v[50:53], v[2:3], off
	global_load_dwordx4 v[46:49], v[2:3], off offset:1024
	global_load_dwordx4 v[62:65], v[2:3], off offset:2048
	global_load_dwordx4 v[58:61], v[2:3], off offset:3072
	s_waitcnt vmcnt(3)
	v_mov_b32_e32 v6, v51
	s_waitcnt vmcnt(2)
	v_mov_b32_e32 v7, v47
	v_mov_b32_e32 v4, v50
	v_mov_b32_e32 v5, v46
	v_pk_mul_f32 v[6:7], v[6:7], v[6:7]
	s_waitcnt vmcnt(1)
	v_mov_b32_e32 v2, v62
	v_pk_fma_f32 v[4:5], v[4:5], v[4:5], v[6:7]
	v_mov_b32_e32 v6, v52
	v_mov_b32_e32 v7, v48
	v_pk_fma_f32 v[4:5], v[6:7], v[6:7], v[4:5]
	v_mov_b32_e32 v6, v53
	v_mov_b32_e32 v7, v49
	v_pk_fma_f32 v[86:87], v[6:7], v[6:7], v[4:5]
	v_mov_b32_e32 v4, v63
	s_waitcnt vmcnt(0)
	v_mov_b32_e32 v5, v59
	v_mov_b32_e32 v3, v58
	v_pk_mul_f32 v[4:5], v[4:5], v[4:5]
	s_nop 0
	v_pk_fma_f32 v[2:3], v[2:3], v[2:3], v[4:5]
	v_mov_b32_e32 v4, v64
	v_mov_b32_e32 v5, v60
	v_pk_fma_f32 v[2:3], v[4:5], v[4:5], v[2:3]
	v_mov_b32_e32 v4, v65
	v_mov_b32_e32 v5, v61
	v_pk_fma_f32 v[90:91], v[4:5], v[4:5], v[2:3]
	v_or_b32_e32 v2, 2, v0
	v_cmp_lt_i32_e32 vcc, 63, v2
	s_nop 1
	v_cndmask_b32_e32 v3, 0, v95, vcc
	v_add_u32_e32 v80, v3, v2
	v_ashrrev_i32_e32 v81, 31, v80
	v_lshlrev_b64 v[2:3], 12, v[80:81]
	v_lshl_add_u64 v[14:15], v[68:69], 0, v[2:3]
	global_load_dwordx4 v[6:9], v[14:15], off
	global_load_dwordx4 v[2:5], v[14:15], off offset:1024
	s_waitcnt vmcnt(1)
	v_mov_b32_e32 v22, v7
	s_waitcnt vmcnt(0)
	v_mov_b32_e32 v23, v3
	v_mov_b32_e32 v16, v6
	v_mov_b32_e32 v17, v2
	v_pk_mul_f32 v[22:23], v[22:23], v[22:23]
	s_nop 0
	v_pk_fma_f32 v[16:17], v[16:17], v[16:17], v[22:23]
	v_mov_b32_e32 v22, v8
	v_mov_b32_e32 v23, v4
	v_pk_fma_f32 v[16:17], v[22:23], v[22:23], v[16:17]
	v_mov_b32_e32 v22, v9
	v_mov_b32_e32 v23, v5
	v_pk_fma_f32 v[76:77], v[22:23], v[22:23], v[16:17]
	global_load_dwordx4 v[22:25], v[14:15], off offset:2048
	s_nop 0
	global_load_dwordx4 v[14:17], v[14:15], off offset:3072
	s_waitcnt vmcnt(1)
	v_mov_b32_e32 v28, v23
	s_waitcnt vmcnt(0)
	v_mov_b32_e32 v29, v15
	v_mov_b32_e32 v26, v22
	v_mov_b32_e32 v27, v14
	v_pk_mul_f32 v[28:29], v[28:29], v[28:29]
	s_nop 0
	v_pk_fma_f32 v[26:27], v[26:27], v[26:27], v[28:29]
	v_mov_b32_e32 v28, v24
	v_mov_b32_e32 v29, v16
	v_pk_fma_f32 v[26:27], v[28:29], v[28:29], v[26:27]
	v_mov_b32_e32 v28, v25
	v_mov_b32_e32 v29, v17
	v_pk_fma_f32 v[78:79], v[28:29], v[28:29], v[26:27]
	v_or_b32_e32 v26, 3, v0
	v_cmp_lt_i32_e32 vcc, 63, v26
	s_nop 1
	v_cndmask_b32_e32 v27, 0, v95, vcc
	v_add_u32_e32 v72, v27, v26
	v_ashrrev_i32_e32 v73, 31, v72
	v_lshlrev_b64 v[26:27], 12, v[72:73]
	v_lshl_add_u64 v[42:43], v[68:69], 0, v[26:27]
	global_load_dwordx4 v[34:37], v[42:43], off
	global_load_dwordx4 v[26:29], v[42:43], off offset:1024
	s_waitcnt vmcnt(1)
	v_mov_b32_e32 v54, v35
	s_waitcnt vmcnt(0)
	v_mov_b32_e32 v55, v27
	v_mov_b32_e32 v44, v34
	v_mov_b32_e32 v45, v26
	v_pk_mul_f32 v[54:55], v[54:55], v[54:55]
	s_nop 0
	v_pk_fma_f32 v[44:45], v[44:45], v[44:45], v[54:55]
	v_mov_b32_e32 v54, v36
	v_mov_b32_e32 v55, v28
	v_pk_fma_f32 v[44:45], v[54:55], v[54:55], v[44:45]
	v_mov_b32_e32 v54, v37
	v_mov_b32_e32 v55, v29
	v_pk_fma_f32 v[84:85], v[54:55], v[54:55], v[44:45]
	global_load_dwordx4 v[54:57], v[42:43], off offset:2048
	s_nop 0
	global_load_dwordx4 v[42:45], v[42:43], off offset:3072
	s_waitcnt vmcnt(1)
	v_mov_b32_e32 v96, v55
	s_waitcnt vmcnt(0)
	v_mov_b32_e32 v97, v43
	v_mov_b32_e32 v88, v54
	v_mov_b32_e32 v89, v42
	v_pk_mul_f32 v[96:97], v[96:97], v[96:97]
	s_nop 0
	v_pk_fma_f32 v[88:89], v[88:89], v[88:89], v[96:97]
	v_mov_b32_e32 v96, v56
	v_mov_b32_e32 v97, v44
	v_pk_fma_f32 v[88:89], v[96:97], v[96:97], v[88:89]
	v_mov_b32_e32 v96, v57
	v_mov_b32_e32 v97, v45
	v_pk_fma_f32 v[88:89], v[96:97], v[96:97], v[88:89]
	v_mov_b32_e32 v96, v86
	v_mov_b32_e32 v97, v70
	v_mov_b32_e32 v70, v87
	v_pk_add_f32 v[70:71], v[96:97], v[70:71]
	v_mov_b32_e32 v86, v90
	v_mov_b32_e32 v87, v82
	v_pk_add_f32 v[70:71], v[70:71], v[86:87]
	v_mov_b32_e32 v82, v91
	v_pk_add_f32 v[70:71], v[70:71], v[82:83]
	ds_bpermute_b32 v83, v224, v71
	ds_bpermute_b32 v82, v224, v70
	s_waitcnt lgkmcnt(0)
; DI unsigned pk2(float lo, float hi) { f32x2 v = {lo, hi}; bf2_t b = __builtin_convertvector(v, bf2_t); return __builtin_bit_cast(unsigned, b); }
; template <int MODE, int MT> DI void norm_rows(const float* src, const float* src2, float* x, int d2, bf16_t* xb, const float* __restrict__ g) {
;     ...
; #pragma unroll
;         for (int o = 32; o >= 1; o >>= 1)
; #pragma unroll
;             for (int q = 0; q < 4; ++q) ss[q] += __shfl_xor(ss[q], o);
; #pragma unroll
;         for (int q = 0; q < 4; ++q) {
;             const int row = wave * (MT * 4) + rb * 4 + q, grow = row + (row >= 64 ? d2 : 0);
;             const float rstd = rsqrtf(ss[q] * (1.f / DM) + 1e-6f);
; #pragma unroll
;             for (int i = 0; i < 4; ++i) {
;                 if (MODE == 0) *(f32x4*)(x + (size_t)grow * DM + i * 256 + lane * 4) = v[q][i];
;                 if (MODE == 2) { f32x4 gg = *(const f32x4*)(g + i * 256 + lane * 4); *(f32x4*)(x + (size_t)grow * DM + i * 256 + lane * 4) = v[q][i] * rstd * gg; }
;                 else { u32x2 o = {pk2(v[q][i][0] * rstd, v[q][i][1] * rstd), pk2(v[q][i][2] * rstd, v[q][i][3] * rstd)}; *(u32x2*)(xb + (size_t)grow * DM + i * 256 + lane * 4) = o; }
;             }
;         }
	v_pk_add_f32 v[70:71], v[70:71], v[82:83]
	ds_bpermute_b32 v83, v228, v71
	ds_bpermute_b32 v82, v228, v70
	s_waitcnt lgkmcnt(0)
	v_pk_add_f32 v[70:71], v[70:71], v[82:83]
	ds_bpermute_b32 v83, v227, v71
	ds_bpermute_b32 v82, v227, v70
	s_waitcnt lgkmcnt(0)
	v_pk_add_f32 v[70:71], v[70:71], v[82:83]
	ds_bpermute_b32 v83, v226, v71
	ds_bpermute_b32 v82, v226, v70
	s_waitcnt lgkmcnt(0)
	v_pk_add_f32 v[70:71], v[70:71], v[82:83]
	ds_bpermute_b32 v83, v225, v71
	ds_bpermute_b32 v82, v225, v70
	s_waitcnt lgkmcnt(0)
	v_pk_add_f32 v[70:71], v[70:71], v[82:83]
	ds_bpermute_b32 v83, v223, v71
	ds_bpermute_b32 v82, v223, v70
	s_waitcnt lgkmcnt(0)
	v_pk_add_f32 v[82:83], v[70:71], v[82:83]
	v_mov_b64_e32 v[70:71], s[0:1]
	v_pk_fma_f32 v[82:83], v[82:83], s[4:5], v[70:71] op_sel_hi:[1,0,0]
	s_nop 0
	v_mul_f32_e32 v86, 0x4b800000, v83
	v_cmp_gt_f32_e64 s[0:1], s3, v83
	v_cmp_gt_f32_e32 vcc, s3, v82
	s_nop 0
	v_cndmask_b32_e64 v83, v83, v86, s[0:1]
	v_rsq_f32_e32 v83, v83
	s_nop 0
	v_mul_f32_e32 v86, 0x45800000, v83
	v_cndmask_b32_e64 v86, v83, v86, s[0:1]
	v_pk_mul_f32 v[10:11], v[10:11], v[86:87] op_sel_hi:[1,0]
	v_pk_mul_f32 v[12:13], v[12:13], v[86:87] op_sel_hi:[1,0]
	v_cvt_pk_f16_f32 v10, v10, v11
	v_cvt_pk_f16_f32 v11, v12, v13
	global_store_dwordx2 v[92:93], v[10:11], off offset:512
	v_pk_mul_f32 v[10:11], v[38:39], v[86:87] op_sel_hi:[1,0]
	v_pk_mul_f32 v[12:13], v[40:41], v[86:87] op_sel_hi:[1,0]
	v_cvt_pk_f16_f32 v10, v10, v11
	v_cvt_pk_f16_f32 v11, v12, v13
	global_store_dwordx2 v[92:93], v[10:11], off offset:1024
	v_pk_mul_f32 v[10:11], v[30:31], v[86:87] op_sel_hi:[1,0]
	v_pk_mul_f32 v[12:13], v[32:33], v[86:87] op_sel_hi:[1,0]
	v_cvt_pk_f16_f32 v10, v10, v11
	v_cvt_pk_f16_f32 v11, v12, v13
	global_store_dwordx2 v[92:93], v[10:11], off offset:1536
	v_mul_f32_e32 v10, 0x4b800000, v82
	v_cndmask_b32_e32 v10, v82, v10, vcc
	v_rsq_f32_e32 v10, v10
	v_pk_mul_f32 v[18:19], v[18:19], v[86:87] op_sel_hi:[1,0]
	v_pk_mul_f32 v[20:21], v[20:21], v[86:87] op_sel_hi:[1,0]
	v_cvt_pk_f16_f32 v18, v18, v19
	v_mul_f32_e32 v11, 0x45800000, v10
	v_cvt_pk_f16_f32 v19, v20, v21
	v_cndmask_b32_e32 v10, v10, v11, vcc
	global_store_dwordx2 v[92:93], v[18:19], off
	v_lshlrev_b64 v[12:13], 11, v[74:75]
	v_pk_mul_f32 v[18:19], v[50:51], v[10:11] op_sel_hi:[1,0]
	v_pk_mul_f32 v[20:21], v[52:53], v[10:11] op_sel_hi:[1,0]
	v_lshl_add_u64 v[12:13], v[66:67], 0, v[12:13]
	v_cvt_pk_f16_f32 v18, v18, v19
	v_cvt_pk_f16_f32 v19, v20, v21
	global_store_dwordx2 v[12:13], v[18:19], off
	v_pk_mul_f32 v[18:19], v[46:47], v[10:11] op_sel_hi:[1,0]
	v_pk_mul_f32 v[20:21], v[48:49], v[10:11] op_sel_hi:[1,0]
	v_cvt_pk_f16_f32 v18, v18, v19
	v_cvt_pk_f16_f32 v19, v20, v21
	global_store_dwordx2 v[12:13], v[18:19], off offset:512
	v_pk_mul_f32 v[18:19], v[62:63], v[10:11] op_sel_hi:[1,0]
	v_pk_mul_f32 v[20:21], v[64:65], v[10:11] op_sel_hi:[1,0]
	v_cvt_pk_f16_f32 v18, v18, v19
	v_cvt_pk_f16_f32 v19, v20, v21
	global_store_dwordx2 v[12:13], v[18:19], off offset:1024
	v_pk_mul_f32 v[18:19], v[58:59], v[10:11] op_sel_hi:[1,0]
	v_pk_mul_f32 v[10:11], v[60:61], v[10:11] op_sel_hi:[1,0]
	v_cvt_pk_f16_f32 v18, v18, v19
	v_cvt_pk_f16_f32 v19, v10, v11
	global_store_dwordx2 v[12:13], v[18:19], off offset:1536
	v_mov_b32_e32 v12, v84
	v_mov_b32_e32 v13, v76
	v_mov_b32_e32 v76, v85
	v_pk_add_f32 v[12:13], v[12:13], v[76:77]
	v_mov_b32_e32 v18, v88
	v_mov_b32_e32 v19, v78
	v_pk_add_f32 v[12:13], v[12:13], v[18:19]
	v_mov_b32_e32 v78, v89
	v_pk_add_f32 v[12:13], v[12:13], v[78:79]
	ds_bpermute_b32 v19, v224, v13
	ds_bpermute_b32 v18, v224, v12
	v_lshlrev_b64 v[10:11], 11, v[80:81]
	v_lshl_add_u64 v[10:11], v[66:67], 0, v[10:11]
	s_waitcnt lgkmcnt(0)
	v_pk_add_f32 v[12:13], v[12:13], v[18:19]
	ds_bpermute_b32 v19, v228, v13
	ds_bpermute_b32 v18, v228, v12
	s_waitcnt lgkmcnt(0)
	v_pk_add_f32 v[12:13], v[12:13], v[18:19]
	ds_bpermute_b32 v19, v227, v13
	ds_bpermute_b32 v18, v227, v12
	s_waitcnt lgkmcnt(0)
	v_pk_add_f32 v[12:13], v[12:13], v[18:19]
	ds_bpermute_b32 v19, v226, v13
	ds_bpermute_b32 v18, v226, v12
	s_waitcnt lgkmcnt(0)
	v_pk_add_f32 v[12:13], v[12:13], v[18:19]
	ds_bpermute_b32 v19, v225, v13
	ds_bpermute_b32 v18, v225, v12
	s_waitcnt lgkmcnt(0)
	v_pk_add_f32 v[12:13], v[12:13], v[18:19]
	ds_bpermute_b32 v19, v223, v13
	ds_bpermute_b32 v18, v223, v12
	s_waitcnt lgkmcnt(0)
; DI unsigned pk2(float lo, float hi) { f32x2 v = {lo, hi}; bf2_t b = __builtin_convertvector(v, bf2_t); return __builtin_bit_cast(unsigned, b); }
; template <int MODE, int MT> DI void norm_rows(const float* src, const float* src2, float* x, int d2, bf16_t* xb, const float* __restrict__ g) {
;     ...
;     for (int rb = 0; rb < MT; ++rb) {
;         f32x4 v[4][4]; float ss[4];
; #pragma unroll
;         for (int q = 0; q < 4; ++q) {
;             const int row = wave * (MT * 4) + rb * 4 + q, grow = row + (row >= 64 ? d2 : 0);
;             const float* s = x + (size_t)grow * DM;
;             if (MODE == 0) { s = src + (size_t)row * DM; if (MT == 3 && row >= 64) s = src2 + (size_t)(row - 64) * DM; }
;             ss[q] = 0.f;
; #pragma unroll
;             for (int i = 0; i < 4; ++i) { v[q][i] = *(const f32x4*)(s + i * 256 + lane * 4); ss[q] += v[q][i][0] * v[q][i][0] + v[q][i][1] * v[q][i][1] + v[q][i][2] * v[q][i][2] + v[q][i][3] * v[q][i][3]; }
;         }
; #pragma unroll
;         for (int o = 32; o >= 1; o >>= 1)
; #pragma unroll
;             for (int q = 0; q < 4; ++q) ss[q] += __shfl_xor(ss[q], o);
; #pragma unroll
;         for (int q = 0; q < 4; ++q) {
;             const int row = wave * (MT * 4) + rb * 4 + q, grow = row + (row >= 64 ? d2 : 0);
;             const float rstd = rsqrtf(ss[q] * (1.f / DM) + 1e-6f);
; #pragma unroll
;             for (int i = 0; i < 4; ++i) {
;                 if (MODE == 0) *(f32x4*)(x + (size_t)grow * DM + i * 256 + lane * 4) = v[q][i];
;                 if (MODE == 2) { f32x4 gg = *(const f32x4*)(g + i * 256 + lane * 4); *(f32x4*)(x + (size_t)grow * DM + i * 256 + lane * 4) = v[q][i] * rstd * gg; }
;                 else { u32x2 o = {pk2(v[q][i][0] * rstd, v[q][i][1] * rstd), pk2(v[q][i][2] * rstd, v[q][i][3] * rstd)}; *(u32x2*)(xb + (size_t)grow * DM + i * 256 + lane * 4) = o; }
;             }
;         }
	v_pk_add_f32 v[12:13], v[12:13], v[18:19]
	s_nop 0
	v_pk_fma_f32 v[12:13], v[12:13], s[4:5], v[70:71] op_sel_hi:[1,0,0]
	s_nop 0
	v_mul_f32_e32 v18, 0x4b800000, v13
	v_cmp_gt_f32_e64 s[0:1], s3, v13
	v_cmp_gt_f32_e32 vcc, s3, v12
	s_nop 0
	v_cndmask_b32_e64 v13, v13, v18, s[0:1]
	v_rsq_f32_e32 v13, v13
	s_nop 0
	v_mul_f32_e32 v18, 0x45800000, v13
	v_cndmask_b32_e64 v18, v13, v18, s[0:1]
	v_pk_mul_f32 v[2:3], v[2:3], v[18:19] op_sel_hi:[1,0]
	v_pk_mul_f32 v[4:5], v[4:5], v[18:19] op_sel_hi:[1,0]
	v_cvt_pk_f16_f32 v2, v2, v3
	v_cvt_pk_f16_f32 v3, v4, v5
	global_store_dwordx2 v[10:11], v[2:3], off offset:512
	v_pk_mul_f32 v[2:3], v[22:23], v[18:19] op_sel_hi:[1,0]
	v_pk_mul_f32 v[4:5], v[24:25], v[18:19] op_sel_hi:[1,0]
	v_cvt_pk_f16_f32 v2, v2, v3
	v_cvt_pk_f16_f32 v3, v4, v5
	global_store_dwordx2 v[10:11], v[2:3], off offset:1024
	v_pk_mul_f32 v[2:3], v[14:15], v[18:19] op_sel_hi:[1,0]
	v_pk_mul_f32 v[4:5], v[16:17], v[18:19] op_sel_hi:[1,0]
	v_cvt_pk_f16_f32 v2, v2, v3
	v_cvt_pk_f16_f32 v3, v4, v5
	global_store_dwordx2 v[10:11], v[2:3], off offset:1536
	v_mul_f32_e32 v2, 0x4b800000, v12
	v_cndmask_b32_e32 v2, v12, v2, vcc
	v_rsq_f32_e32 v2, v2
	v_pk_mul_f32 v[6:7], v[6:7], v[18:19] op_sel_hi:[1,0]
	v_pk_mul_f32 v[8:9], v[8:9], v[18:19] op_sel_hi:[1,0]
	v_cvt_pk_f16_f32 v6, v6, v7
	v_mul_f32_e32 v3, 0x45800000, v2
	v_cvt_pk_f16_f32 v7, v8, v9
	v_cndmask_b32_e32 v2, v2, v3, vcc
	global_store_dwordx2 v[10:11], v[6:7], off
	v_lshlrev_b64 v[4:5], 11, v[72:73]
	v_pk_mul_f32 v[6:7], v[34:35], v[2:3] op_sel_hi:[1,0]
	v_pk_mul_f32 v[8:9], v[36:37], v[2:3] op_sel_hi:[1,0]
	v_lshl_add_u64 v[4:5], v[66:67], 0, v[4:5]
	v_cvt_pk_f16_f32 v6, v6, v7
	v_cvt_pk_f16_f32 v7, v8, v9
	global_store_dwordx2 v[4:5], v[6:7], off
	v_pk_mul_f32 v[6:7], v[26:27], v[2:3] op_sel_hi:[1,0]
	v_pk_mul_f32 v[8:9], v[28:29], v[2:3] op_sel_hi:[1,0]
	v_cvt_pk_f16_f32 v6, v6, v7
	v_cvt_pk_f16_f32 v7, v8, v9
	global_store_dwordx2 v[4:5], v[6:7], off offset:512
	v_pk_mul_f32 v[6:7], v[54:55], v[2:3] op_sel_hi:[1,0]
	v_pk_mul_f32 v[8:9], v[56:57], v[2:3] op_sel_hi:[1,0]
	v_cvt_pk_f16_f32 v6, v6, v7
	v_cvt_pk_f16_f32 v7, v8, v9
	global_store_dwordx2 v[4:5], v[6:7], off offset:1024
	v_pk_mul_f32 v[6:7], v[42:43], v[2:3] op_sel_hi:[1,0]
	v_pk_mul_f32 v[2:3], v[44:45], v[2:3] op_sel_hi:[1,0]
	v_cmp_lt_i32_e32 vcc, 4, v94
	v_cvt_pk_f16_f32 v6, v6, v7
	v_cvt_pk_f16_f32 v7, v2, v3
	v_cndmask_b32_e32 v2, 0, v95, vcc
	v_add_u32_e32 v0, v2, v0
	v_add_u32_e32 v92, 4, v0
	v_ashrrev_i32_e32 v93, 31, v92
	v_lshlrev_b64 v[2:3], 12, v[92:93]
	global_store_dwordx2 v[4:5], v[6:7], off offset:1536
	v_lshl_add_u64 v[2:3], v[68:69], 0, v[2:3]
	global_load_dwordx4 v[18:21], v[2:3], off
	global_load_dwordx4 v[10:13], v[2:3], off offset:1024
	global_load_dwordx4 v[34:37], v[2:3], off offset:2048
	global_load_dwordx4 v[26:29], v[2:3], off offset:3072
	v_add_u32_e32 v74, 5, v0
	v_ashrrev_i32_e32 v75, 31, v74
	v_add_u32_e32 v82, 6, v0
	v_ashrrev_i32_e32 v83, 31, v82
	v_add_u32_e32 v72, 7, v0
	v_ashrrev_i32_e32 v73, 31, v72
	v_lshlrev_b64 v[92:93], 11, v[92:93]
	v_lshl_add_u64 v[92:93], v[66:67], 0, v[92:93]
	s_waitcnt vmcnt(3)
	v_mov_b32_e32 v6, v19
	s_waitcnt vmcnt(2)
	v_mov_b32_e32 v7, v11
	v_mov_b32_e32 v4, v18
	v_mov_b32_e32 v5, v10
	v_pk_mul_f32 v[6:7], v[6:7], v[6:7]
	s_waitcnt vmcnt(1)
	v_mov_b32_e32 v2, v34
	v_pk_fma_f32 v[4:5], v[4:5], v[4:5], v[6:7]
	v_mov_b32_e32 v6, v20
	v_mov_b32_e32 v7, v12
	v_pk_fma_f32 v[4:5], v[6:7], v[6:7], v[4:5]
	v_mov_b32_e32 v6, v21
	v_mov_b32_e32 v7, v13
	v_pk_fma_f32 v[78:79], v[6:7], v[6:7], v[4:5]
	v_mov_b32_e32 v4, v35
	s_waitcnt vmcnt(0)
	v_mov_b32_e32 v5, v27
	v_mov_b32_e32 v3, v26
	v_pk_mul_f32 v[4:5], v[4:5], v[4:5]
	s_nop 0
	v_pk_fma_f32 v[2:3], v[2:3], v[2:3], v[4:5]
	v_mov_b32_e32 v4, v36
	v_mov_b32_e32 v5, v28
	v_pk_fma_f32 v[2:3], v[4:5], v[4:5], v[2:3]
	v_mov_b32_e32 v4, v37
	v_mov_b32_e32 v5, v29
	v_pk_fma_f32 v[84:85], v[4:5], v[4:5], v[2:3]
	v_lshlrev_b64 v[2:3], 12, v[74:75]
	v_lshl_add_u64 v[2:3], v[68:69], 0, v[2:3]
	global_load_dwordx4 v[46:49], v[2:3], off
	global_load_dwordx4 v[42:45], v[2:3], off offset:1024
	global_load_dwordx4 v[54:57], v[2:3], off offset:2048
	global_load_dwordx4 v[50:53], v[2:3], off offset:3072
	s_waitcnt vmcnt(3)
	v_mov_b32_e32 v6, v47
	s_waitcnt vmcnt(2)
	v_mov_b32_e32 v7, v43
	v_mov_b32_e32 v4, v46
	v_mov_b32_e32 v5, v42
	v_pk_mul_f32 v[6:7], v[6:7], v[6:7]
	s_waitcnt vmcnt(1)
	v_mov_b32_e32 v2, v54
	v_pk_fma_f32 v[4:5], v[4:5], v[4:5], v[6:7]
	v_mov_b32_e32 v6, v48
	v_mov_b32_e32 v7, v44
	v_pk_fma_f32 v[4:5], v[6:7], v[6:7], v[4:5]
	v_mov_b32_e32 v6, v49
	v_mov_b32_e32 v7, v45
	v_pk_fma_f32 v[88:89], v[6:7], v[6:7], v[4:5]
	v_mov_b32_e32 v4, v55
	s_waitcnt vmcnt(0)
	v_mov_b32_e32 v5, v51
	v_mov_b32_e32 v3, v50
	v_pk_mul_f32 v[4:5], v[4:5], v[4:5]
	s_nop 0
	v_pk_fma_f32 v[2:3], v[2:3], v[2:3], v[4:5]
	v_mov_b32_e32 v4, v56
	v_mov_b32_e32 v5, v52
	v_pk_fma_f32 v[2:3], v[4:5], v[4:5], v[2:3]
	v_mov_b32_e32 v4, v57
	v_mov_b32_e32 v5, v53
	v_pk_fma_f32 v[90:91], v[4:5], v[4:5], v[2:3]
	v_lshlrev_b64 v[2:3], 12, v[82:83]
	v_lshl_add_u64 v[14:15], v[68:69], 0, v[2:3]
	global_load_dwordx4 v[6:9], v[14:15], off
	global_load_dwordx4 v[2:5], v[14:15], off offset:1024
	s_waitcnt vmcnt(1)
	v_mov_b32_e32 v22, v7
	s_waitcnt vmcnt(0)
	v_mov_b32_e32 v23, v3
	v_mov_b32_e32 v16, v6
	v_mov_b32_e32 v17, v2
	v_pk_mul_f32 v[22:23], v[22:23], v[22:23]
	s_nop 0
	v_pk_fma_f32 v[16:17], v[16:17], v[16:17], v[22:23]
	v_mov_b32_e32 v22, v8
	v_mov_b32_e32 v23, v4
	v_pk_fma_f32 v[16:17], v[22:23], v[22:23], v[16:17]
	v_mov_b32_e32 v22, v9
	v_mov_b32_e32 v23, v5
	v_pk_fma_f32 v[76:77], v[22:23], v[22:23], v[16:17]
	global_load_dwordx4 v[22:25], v[14:15], off offset:2048
	s_nop 0
	global_load_dwordx4 v[14:17], v[14:15], off offset:3072
	s_waitcnt vmcnt(1)
; DI unsigned pk2(float lo, float hi) { f32x2 v = {lo, hi}; bf2_t b = __builtin_convertvector(v, bf2_t); return __builtin_bit_cast(unsigned, b); }
; template <int MODE, int MT> DI void norm_rows(const float* src, const float* src2, float* x, int d2, bf16_t* xb, const float* __restrict__ g) {
;     ...
;     for (int rb = 0; rb < MT; ++rb) {
;         f32x4 v[4][4]; float ss[4];
; #pragma unroll
;         for (int q = 0; q < 4; ++q) {
;             const int row = wave * (MT * 4) + rb * 4 + q, grow = row + (row >= 64 ? d2 : 0);
;             const float* s = x + (size_t)grow * DM;
;             if (MODE == 0) { s = src + (size_t)row * DM; if (MT == 3 && row >= 64) s = src2 + (size_t)(row - 64) * DM; }
;             ss[q] = 0.f;
; #pragma unroll
;             for (int i = 0; i < 4; ++i) { v[q][i] = *(const f32x4*)(s + i * 256 + lane * 4); ss[q] += v[q][i][0] * v[q][i][0] + v[q][i][1] * v[q][i][1] + v[q][i][2] * v[q][i][2] + v[q][i][3] * v[q][i][3]; }
;         }
; #pragma unroll
;         for (int o = 32; o >= 1; o >>= 1)
; #pragma unroll
;             for (int q = 0; q < 4; ++q) ss[q] += __shfl_xor(ss[q], o);
; #pragma unroll
;         for (int q = 0; q < 4; ++q) {
;             const int row = wave * (MT * 4) + rb * 4 + q, grow = row + (row >= 64 ? d2 : 0);
;             const float rstd = rsqrtf(ss[q] * (1.f / DM) + 1e-6f);
; #pragma unroll
;             for (int i = 0; i < 4; ++i) {
;                 if (MODE == 0) *(f32x4*)(x + (size_t)grow * DM + i * 256 + lane * 4) = v[q][i];
;                 if (MODE == 2) { f32x4 gg = *(const f32x4*)(g + i * 256 + lane * 4); *(f32x4*)(x + (size_t)grow * DM + i * 256 + lane * 4) = v[q][i] * rstd * gg; }
;                 else { u32x2 o = {pk2(v[q][i][0] * rstd, v[q][i][1] * rstd), pk2(v[q][i][2] * rstd, v[q][i][3] * rstd)}; *(u32x2*)(xb + (size_t)grow * DM + i * 256 + lane * 4) = o; }
;             }
;         }
	v_mov_b32_e32 v32, v23
	s_waitcnt vmcnt(0)
	v_mov_b32_e32 v33, v15
	v_mov_b32_e32 v30, v22
	v_mov_b32_e32 v31, v14
	v_pk_mul_f32 v[32:33], v[32:33], v[32:33]
	s_nop 0
	v_pk_fma_f32 v[30:31], v[30:31], v[30:31], v[32:33]
	v_mov_b32_e32 v32, v24
	v_mov_b32_e32 v33, v16
	v_pk_fma_f32 v[30:31], v[32:33], v[32:33], v[30:31]
	v_mov_b32_e32 v32, v25
	v_mov_b32_e32 v33, v17
	v_pk_fma_f32 v[80:81], v[32:33], v[32:33], v[30:31]
	v_lshlrev_b64 v[30:31], 12, v[72:73]
	v_lshl_add_u64 v[58:59], v[68:69], 0, v[30:31]
	global_load_dwordx4 v[38:41], v[58:59], off
	global_load_dwordx4 v[30:33], v[58:59], off offset:1024
	s_waitcnt vmcnt(1)
	v_mov_b32_e32 v62, v39
	s_waitcnt vmcnt(0)
	v_mov_b32_e32 v63, v31
	v_mov_b32_e32 v60, v38
	v_mov_b32_e32 v61, v30
	v_pk_mul_f32 v[62:63], v[62:63], v[62:63]
	s_nop 0
	v_pk_fma_f32 v[60:61], v[60:61], v[60:61], v[62:63]
	v_mov_b32_e32 v62, v40
	v_mov_b32_e32 v63, v32
	v_pk_fma_f32 v[60:61], v[62:63], v[62:63], v[60:61]
	v_mov_b32_e32 v62, v41
	v_mov_b32_e32 v63, v33
	v_pk_fma_f32 v[86:87], v[62:63], v[62:63], v[60:61]
	global_load_dwordx4 v[62:65], v[58:59], off offset:2048
	s_nop 0
	global_load_dwordx4 v[58:61], v[58:59], off offset:3072
	s_waitcnt vmcnt(1)
	v_mov_b32_e32 v96, v63
	s_waitcnt vmcnt(0)
	v_mov_b32_e32 v97, v59
	v_mov_b32_e32 v94, v62
	v_mov_b32_e32 v95, v58
	v_pk_mul_f32 v[96:97], v[96:97], v[96:97]
	s_nop 0
	v_pk_fma_f32 v[94:95], v[94:95], v[94:95], v[96:97]
	v_mov_b32_e32 v96, v64
	v_mov_b32_e32 v97, v60
	v_pk_fma_f32 v[94:95], v[96:97], v[96:97], v[94:95]
	v_mov_b32_e32 v96, v65
	v_mov_b32_e32 v97, v61
	v_pk_fma_f32 v[94:95], v[96:97], v[96:97], v[94:95]
	v_mov_b32_e32 v96, v88
	v_mov_b32_e32 v97, v78
	v_mov_b32_e32 v78, v89
	v_pk_add_f32 v[78:79], v[96:97], v[78:79]
	v_mov_b32_e32 v88, v90
	v_mov_b32_e32 v89, v84
	v_pk_add_f32 v[78:79], v[78:79], v[88:89]
	v_mov_b32_e32 v84, v91
	v_pk_add_f32 v[78:79], v[78:79], v[84:85]
	ds_bpermute_b32 v85, v224, v79
	ds_bpermute_b32 v84, v224, v78
	v_add_u32_e32 v90, 8, v0
	v_ashrrev_i32_e32 v91, 31, v90
	s_waitcnt lgkmcnt(0)
	v_pk_add_f32 v[78:79], v[78:79], v[84:85]
	ds_bpermute_b32 v85, v228, v79
	ds_bpermute_b32 v84, v228, v78
	s_waitcnt lgkmcnt(0)
	v_pk_add_f32 v[78:79], v[78:79], v[84:85]
	ds_bpermute_b32 v85, v227, v79
	ds_bpermute_b32 v84, v227, v78
	s_waitcnt lgkmcnt(0)
	v_pk_add_f32 v[78:79], v[78:79], v[84:85]
	ds_bpermute_b32 v85, v226, v79
	ds_bpermute_b32 v84, v226, v78
	s_waitcnt lgkmcnt(0)
	v_pk_add_f32 v[78:79], v[78:79], v[84:85]
	ds_bpermute_b32 v85, v225, v79
	ds_bpermute_b32 v84, v225, v78
	s_waitcnt lgkmcnt(0)
	v_pk_add_f32 v[78:79], v[78:79], v[84:85]
	ds_bpermute_b32 v85, v223, v79
	ds_bpermute_b32 v84, v223, v78
	s_waitcnt lgkmcnt(0)
	v_pk_add_f32 v[78:79], v[78:79], v[84:85]
	s_nop 0
	v_pk_fma_f32 v[78:79], v[78:79], s[4:5], v[70:71] op_sel_hi:[1,0,0]
	s_nop 0
	v_mul_f32_e32 v84, 0x4b800000, v79
	v_cmp_gt_f32_e64 s[0:1], s3, v79
	v_cmp_gt_f32_e32 vcc, s3, v78
	s_nop 0
	v_cndmask_b32_e64 v79, v79, v84, s[0:1]
	v_rsq_f32_e32 v79, v79
	s_nop 0
	v_mul_f32_e32 v84, 0x45800000, v79
	v_cndmask_b32_e64 v84, v79, v84, s[0:1]
	v_pk_mul_f32 v[10:11], v[10:11], v[84:85] op_sel_hi:[1,0]
	v_pk_mul_f32 v[12:13], v[12:13], v[84:85] op_sel_hi:[1,0]
	v_cvt_pk_f16_f32 v10, v10, v11
	v_cvt_pk_f16_f32 v11, v12, v13
	global_store_dwordx2 v[92:93], v[10:11], off offset:512
	v_pk_mul_f32 v[10:11], v[34:35], v[84:85] op_sel_hi:[1,0]
	v_pk_mul_f32 v[12:13], v[36:37], v[84:85] op_sel_hi:[1,0]
	v_cvt_pk_f16_f32 v10, v10, v11
	v_cvt_pk_f16_f32 v11, v12, v13
	global_store_dwordx2 v[92:93], v[10:11], off offset:1024
	v_pk_mul_f32 v[10:11], v[26:27], v[84:85] op_sel_hi:[1,0]
	v_pk_mul_f32 v[12:13], v[28:29], v[84:85] op_sel_hi:[1,0]
	v_cvt_pk_f16_f32 v10, v10, v11
	v_cvt_pk_f16_f32 v11, v12, v13
	global_store_dwordx2 v[92:93], v[10:11], off offset:1536
	v_mul_f32_e32 v10, 0x4b800000, v78
	v_cndmask_b32_e32 v10, v78, v10, vcc
	v_rsq_f32_e32 v10, v10
	v_pk_mul_f32 v[18:19], v[18:19], v[84:85] op_sel_hi:[1,0]
	v_pk_mul_f32 v[20:21], v[20:21], v[84:85] op_sel_hi:[1,0]
	v_cvt_pk_f16_f32 v18, v18, v19
	v_mul_f32_e32 v11, 0x45800000, v10
	v_cvt_pk_f16_f32 v19, v20, v21
	v_cndmask_b32_e32 v10, v10, v11, vcc
	global_store_dwordx2 v[92:93], v[18:19], off
	v_lshlrev_b64 v[12:13], 11, v[74:75]
	v_pk_mul_f32 v[18:19], v[46:47], v[10:11] op_sel_hi:[1,0]
	v_pk_mul_f32 v[20:21], v[48:49], v[10:11] op_sel_hi:[1,0]
	v_lshl_add_u64 v[12:13], v[66:67], 0, v[12:13]
	v_cvt_pk_f16_f32 v18, v18, v19
	v_cvt_pk_f16_f32 v19, v20, v21
	global_store_dwordx2 v[12:13], v[18:19], off
	v_pk_mul_f32 v[18:19], v[42:43], v[10:11] op_sel_hi:[1,0]
	v_pk_mul_f32 v[20:21], v[44:45], v[10:11] op_sel_hi:[1,0]
	v_cvt_pk_f16_f32 v18, v18, v19
	v_cvt_pk_f16_f32 v19, v20, v21
	global_store_dwordx2 v[12:13], v[18:19], off offset:512
	v_pk_mul_f32 v[18:19], v[54:55], v[10:11] op_sel_hi:[1,0]
	v_pk_mul_f32 v[20:21], v[56:57], v[10:11] op_sel_hi:[1,0]
	v_cvt_pk_f16_f32 v18, v18, v19
	v_cvt_pk_f16_f32 v19, v20, v21
	global_store_dwordx2 v[12:13], v[18:19], off offset:1024
	v_pk_mul_f32 v[18:19], v[50:51], v[10:11] op_sel_hi:[1,0]
	v_pk_mul_f32 v[10:11], v[52:53], v[10:11] op_sel_hi:[1,0]
	v_cvt_pk_f16_f32 v18, v18, v19
	v_cvt_pk_f16_f32 v19, v10, v11
	global_store_dwordx2 v[12:13], v[18:19], off offset:1536
	v_mov_b32_e32 v12, v86
	v_mov_b32_e32 v13, v76
	v_mov_b32_e32 v76, v87
	v_pk_add_f32 v[12:13], v[12:13], v[76:77]
	v_mov_b32_e32 v18, v94
	v_mov_b32_e32 v19, v80
	v_pk_add_f32 v[12:13], v[12:13], v[18:19]
	v_mov_b32_e32 v80, v95
	v_pk_add_f32 v[12:13], v[12:13], v[80:81]
	ds_bpermute_b32 v19, v224, v13
	ds_bpermute_b32 v18, v224, v12
	v_lshlrev_b64 v[10:11], 11, v[82:83]
	v_lshl_add_u64 v[10:11], v[66:67], 0, v[10:11]
	v_add_u32_e32 v74, 9, v0
	v_ashrrev_i32_e32 v75, 31, v74
	s_waitcnt lgkmcnt(0)
; DI unsigned pk2(float lo, float hi) { f32x2 v = {lo, hi}; bf2_t b = __builtin_convertvector(v, bf2_t); return __builtin_bit_cast(unsigned, b); }
; template <int MODE, int MT> DI void norm_rows(const float* src, const float* src2, float* x, int d2, bf16_t* xb, const float* __restrict__ g) {
;     ...
;     for (int rb = 0; rb < MT; ++rb) {
;         f32x4 v[4][4]; float ss[4];
; #pragma unroll
;         for (int q = 0; q < 4; ++q) {
;             const int row = wave * (MT * 4) + rb * 4 + q, grow = row + (row >= 64 ? d2 : 0);
;             const float* s = x + (size_t)grow * DM;
;             if (MODE == 0) { s = src + (size_t)row * DM; if (MT == 3 && row >= 64) s = src2 + (size_t)(row - 64) * DM; }
;             ss[q] = 0.f;
; #pragma unroll
;             for (int i = 0; i < 4; ++i) { v[q][i] = *(const f32x4*)(s + i * 256 + lane * 4); ss[q] += v[q][i][0] * v[q][i][0] + v[q][i][1] * v[q][i][1] + v[q][i][2] * v[q][i][2] + v[q][i][3] * v[q][i][3]; }
;         }
; #pragma unroll
;         for (int o = 32; o >= 1; o >>= 1)
; #pragma unroll
;             for (int q = 0; q < 4; ++q) ss[q] += __shfl_xor(ss[q], o);
; #pragma unroll
;         for (int q = 0; q < 4; ++q) {
;             const int row = wave * (MT * 4) + rb * 4 + q, grow = row + (row >= 64 ? d2 : 0);
;             const float rstd = rsqrtf(ss[q] * (1.f / DM) + 1e-6f);
; #pragma unroll
;             for (int i = 0; i < 4; ++i) {
;                 if (MODE == 0) *(f32x4*)(x + (size_t)grow * DM + i * 256 + lane * 4) = v[q][i];
;                 if (MODE == 2) { f32x4 gg = *(const f32x4*)(g + i * 256 + lane * 4); *(f32x4*)(x + (size_t)grow * DM + i * 256 + lane * 4) = v[q][i] * rstd * gg; }
;                 else { u32x2 o = {pk2(v[q][i][0] * rstd, v[q][i][1] * rstd), pk2(v[q][i][2] * rstd, v[q][i][3] * rstd)}; *(u32x2*)(xb + (size_t)grow * DM + i * 256 + lane * 4) = o; }
;             }
;         }
	v_pk_add_f32 v[12:13], v[12:13], v[18:19]
	ds_bpermute_b32 v19, v228, v13
	ds_bpermute_b32 v18, v228, v12
	v_add_u32_e32 v82, 10, v0
	v_ashrrev_i32_e32 v83, 31, v82
	s_waitcnt lgkmcnt(0)
	v_pk_add_f32 v[12:13], v[12:13], v[18:19]
	ds_bpermute_b32 v19, v227, v13
	ds_bpermute_b32 v18, v227, v12
	s_waitcnt lgkmcnt(0)
	v_pk_add_f32 v[12:13], v[12:13], v[18:19]
	ds_bpermute_b32 v19, v226, v13
	ds_bpermute_b32 v18, v226, v12
	s_waitcnt lgkmcnt(0)
	v_pk_add_f32 v[12:13], v[12:13], v[18:19]
	ds_bpermute_b32 v19, v225, v13
	ds_bpermute_b32 v18, v225, v12
	s_waitcnt lgkmcnt(0)
	v_pk_add_f32 v[12:13], v[12:13], v[18:19]
	ds_bpermute_b32 v19, v223, v13
	ds_bpermute_b32 v18, v223, v12
	s_waitcnt lgkmcnt(0)
	v_pk_add_f32 v[12:13], v[12:13], v[18:19]
	s_nop 0
	v_pk_fma_f32 v[12:13], v[12:13], s[4:5], v[70:71] op_sel_hi:[1,0,0]
	s_nop 0
	v_mul_f32_e32 v18, 0x4b800000, v13
	v_cmp_gt_f32_e64 s[0:1], s3, v13
	v_cmp_gt_f32_e32 vcc, s3, v12
	s_nop 0
	v_cndmask_b32_e64 v13, v13, v18, s[0:1]
	v_rsq_f32_e32 v13, v13
	s_nop 0
	v_mul_f32_e32 v18, 0x45800000, v13
	v_cndmask_b32_e64 v18, v13, v18, s[0:1]
	v_pk_mul_f32 v[2:3], v[2:3], v[18:19] op_sel_hi:[1,0]
	v_pk_mul_f32 v[4:5], v[4:5], v[18:19] op_sel_hi:[1,0]
	v_cvt_pk_f16_f32 v2, v2, v3
	v_cvt_pk_f16_f32 v3, v4, v5
	global_store_dwordx2 v[10:11], v[2:3], off offset:512
	v_pk_mul_f32 v[2:3], v[22:23], v[18:19] op_sel_hi:[1,0]
	v_pk_mul_f32 v[4:5], v[24:25], v[18:19] op_sel_hi:[1,0]
	v_cvt_pk_f16_f32 v2, v2, v3
	v_cvt_pk_f16_f32 v3, v4, v5
	global_store_dwordx2 v[10:11], v[2:3], off offset:1024
	v_pk_mul_f32 v[2:3], v[14:15], v[18:19] op_sel_hi:[1,0]
	v_pk_mul_f32 v[4:5], v[16:17], v[18:19] op_sel_hi:[1,0]
	v_cvt_pk_f16_f32 v2, v2, v3
	v_cvt_pk_f16_f32 v3, v4, v5
	global_store_dwordx2 v[10:11], v[2:3], off offset:1536
	v_mul_f32_e32 v2, 0x4b800000, v12
	v_cndmask_b32_e32 v2, v12, v2, vcc
	v_rsq_f32_e32 v2, v2
	v_pk_mul_f32 v[6:7], v[6:7], v[18:19] op_sel_hi:[1,0]
	v_pk_mul_f32 v[8:9], v[8:9], v[18:19] op_sel_hi:[1,0]
	v_cvt_pk_f16_f32 v6, v6, v7
	v_mul_f32_e32 v3, 0x45800000, v2
	v_cvt_pk_f16_f32 v7, v8, v9
	v_cndmask_b32_e32 v2, v2, v3, vcc
	global_store_dwordx2 v[10:11], v[6:7], off
	v_lshlrev_b64 v[4:5], 11, v[72:73]
	v_pk_mul_f32 v[6:7], v[38:39], v[2:3] op_sel_hi:[1,0]
	v_pk_mul_f32 v[8:9], v[40:41], v[2:3] op_sel_hi:[1,0]
	v_lshl_add_u64 v[4:5], v[66:67], 0, v[4:5]
	v_cvt_pk_f16_f32 v6, v6, v7
	v_cvt_pk_f16_f32 v7, v8, v9
	global_store_dwordx2 v[4:5], v[6:7], off
	v_pk_mul_f32 v[6:7], v[30:31], v[2:3] op_sel_hi:[1,0]
	v_pk_mul_f32 v[8:9], v[32:33], v[2:3] op_sel_hi:[1,0]
	v_cvt_pk_f16_f32 v6, v6, v7
	v_cvt_pk_f16_f32 v7, v8, v9
	global_store_dwordx2 v[4:5], v[6:7], off offset:512
	v_pk_mul_f32 v[6:7], v[62:63], v[2:3] op_sel_hi:[1,0]
	v_pk_mul_f32 v[8:9], v[64:65], v[2:3] op_sel_hi:[1,0]
	v_cvt_pk_f16_f32 v6, v6, v7
	v_cvt_pk_f16_f32 v7, v8, v9
	global_store_dwordx2 v[4:5], v[6:7], off offset:1024
	v_pk_mul_f32 v[6:7], v[58:59], v[2:3] op_sel_hi:[1,0]
	v_pk_mul_f32 v[2:3], v[60:61], v[2:3] op_sel_hi:[1,0]
	v_cvt_pk_f16_f32 v6, v6, v7
	v_cvt_pk_f16_f32 v7, v2, v3
	v_lshlrev_b64 v[2:3], 12, v[90:91]
	global_store_dwordx2 v[4:5], v[6:7], off offset:1536
	v_lshl_add_u64 v[2:3], v[68:69], 0, v[2:3]
	global_load_dwordx4 v[18:21], v[2:3], off
	global_load_dwordx4 v[10:13], v[2:3], off offset:1024
	global_load_dwordx4 v[34:37], v[2:3], off offset:2048
	global_load_dwordx4 v[26:29], v[2:3], off offset:3072
	v_add_u32_e32 v72, 11, v0
	v_ashrrev_i32_e32 v73, 31, v72
	v_lshlrev_b64 v[90:91], 11, v[90:91]
	v_lshl_add_u64 v[90:91], v[66:67], 0, v[90:91]
	s_waitcnt vmcnt(3)
	v_mov_b32_e32 v6, v19
	s_waitcnt vmcnt(2)
	v_mov_b32_e32 v7, v11
	v_mov_b32_e32 v4, v18
	v_mov_b32_e32 v5, v10
	v_pk_mul_f32 v[6:7], v[6:7], v[6:7]
	s_waitcnt vmcnt(1)
	v_mov_b32_e32 v2, v34
	v_pk_fma_f32 v[4:5], v[4:5], v[4:5], v[6:7]
	v_mov_b32_e32 v6, v20
	v_mov_b32_e32 v7, v12
	v_pk_fma_f32 v[4:5], v[6:7], v[6:7], v[4:5]
	v_mov_b32_e32 v6, v21
	v_mov_b32_e32 v7, v13
	v_pk_fma_f32 v[78:79], v[6:7], v[6:7], v[4:5]
	v_mov_b32_e32 v4, v35
	s_waitcnt vmcnt(0)
	v_mov_b32_e32 v5, v27
	v_mov_b32_e32 v3, v26
	v_pk_mul_f32 v[4:5], v[4:5], v[4:5]
	s_nop 0
	v_pk_fma_f32 v[2:3], v[2:3], v[2:3], v[4:5]
	v_mov_b32_e32 v4, v36
	v_mov_b32_e32 v5, v28
	v_pk_fma_f32 v[2:3], v[4:5], v[4:5], v[2:3]
	v_mov_b32_e32 v4, v37
	v_mov_b32_e32 v5, v29
	v_pk_fma_f32 v[84:85], v[4:5], v[4:5], v[2:3]
	v_lshlrev_b64 v[2:3], 12, v[74:75]
	v_lshl_add_u64 v[2:3], v[68:69], 0, v[2:3]
	global_load_dwordx4 v[46:49], v[2:3], off
	global_load_dwordx4 v[42:45], v[2:3], off offset:1024
	global_load_dwordx4 v[54:57], v[2:3], off offset:2048
	global_load_dwordx4 v[50:53], v[2:3], off offset:3072
	s_waitcnt vmcnt(3)
	v_mov_b32_e32 v6, v47
	s_waitcnt vmcnt(2)
	v_mov_b32_e32 v7, v43
	v_mov_b32_e32 v4, v46
	v_mov_b32_e32 v5, v42
	v_pk_mul_f32 v[6:7], v[6:7], v[6:7]
	s_waitcnt vmcnt(1)
	v_mov_b32_e32 v2, v54
	v_pk_fma_f32 v[4:5], v[4:5], v[4:5], v[6:7]
	v_mov_b32_e32 v6, v48
	v_mov_b32_e32 v7, v44
	v_pk_fma_f32 v[4:5], v[6:7], v[6:7], v[4:5]
	v_mov_b32_e32 v6, v49
	v_mov_b32_e32 v7, v45
	v_pk_fma_f32 v[86:87], v[6:7], v[6:7], v[4:5]
	v_mov_b32_e32 v4, v55
	s_waitcnt vmcnt(0)
	v_mov_b32_e32 v5, v51
	v_mov_b32_e32 v3, v50
	v_pk_mul_f32 v[4:5], v[4:5], v[4:5]
	s_nop 0
	v_pk_fma_f32 v[2:3], v[2:3], v[2:3], v[4:5]
	v_mov_b32_e32 v4, v56
	v_mov_b32_e32 v5, v52
	v_pk_fma_f32 v[2:3], v[4:5], v[4:5], v[2:3]
	v_mov_b32_e32 v4, v57
	v_mov_b32_e32 v5, v53
	v_pk_fma_f32 v[88:89], v[4:5], v[4:5], v[2:3]
	v_lshlrev_b64 v[2:3], 12, v[82:83]
	v_lshl_add_u64 v[14:15], v[68:69], 0, v[2:3]
	global_load_dwordx4 v[6:9], v[14:15], off
	global_load_dwordx4 v[2:5], v[14:15], off offset:1024
	s_waitcnt vmcnt(1)
; DI unsigned pk2(float lo, float hi) { f32x2 v = {lo, hi}; bf2_t b = __builtin_convertvector(v, bf2_t); return __builtin_bit_cast(unsigned, b); }
; template <int MODE, int MT> DI void norm_rows(const float* src, const float* src2, float* x, int d2, bf16_t* xb, const float* __restrict__ g) {
;     ...
;     for (int rb = 0; rb < MT; ++rb) {
;         f32x4 v[4][4]; float ss[4];
; #pragma unroll
;         for (int q = 0; q < 4; ++q) {
;             const int row = wave * (MT * 4) + rb * 4 + q, grow = row + (row >= 64 ? d2 : 0);
;             const float* s = x + (size_t)grow * DM;
;             if (MODE == 0) { s = src + (size_t)row * DM; if (MT == 3 && row >= 64) s = src2 + (size_t)(row - 64) * DM; }
;             ss[q] = 0.f;
; #pragma unroll
;             for (int i = 0; i < 4; ++i) { v[q][i] = *(const f32x4*)(s + i * 256 + lane * 4); ss[q] += v[q][i][0] * v[q][i][0] + v[q][i][1] * v[q][i][1] + v[q][i][2] * v[q][i][2] + v[q][i][3] * v[q][i][3]; }
;         }
; #pragma unroll
;         for (int o = 32; o >= 1; o >>= 1)
; #pragma unroll
;             for (int q = 0; q < 4; ++q) ss[q] += __shfl_xor(ss[q], o);
; #pragma unroll
;         for (int q = 0; q < 4; ++q) {
;             const int row = wave * (MT * 4) + rb * 4 + q, grow = row + (row >= 64 ? d2 : 0);
;             const float rstd = rsqrtf(ss[q] * (1.f / DM) + 1e-6f);
; #pragma unroll
;             for (int i = 0; i < 4; ++i) {
;                 if (MODE == 0) *(f32x4*)(x + (size_t)grow * DM + i * 256 + lane * 4) = v[q][i];
;                 if (MODE == 2) { f32x4 gg = *(const f32x4*)(g + i * 256 + lane * 4); *(f32x4*)(x + (size_t)grow * DM + i * 256 + lane * 4) = v[q][i] * rstd * gg; }
;                 else { u32x2 o = {pk2(v[q][i][0] * rstd, v[q][i][1] * rstd), pk2(v[q][i][2] * rstd, v[q][i][3] * rstd)}; *(u32x2*)(xb + (size_t)grow * DM + i * 256 + lane * 4) = o; }
;             }
;         }
	v_mov_b32_e32 v22, v7
	s_waitcnt vmcnt(0)
	v_mov_b32_e32 v23, v3
	v_mov_b32_e32 v16, v6
	v_mov_b32_e32 v17, v2
	v_pk_mul_f32 v[22:23], v[22:23], v[22:23]
	s_nop 0
	v_pk_fma_f32 v[16:17], v[16:17], v[16:17], v[22:23]
	v_mov_b32_e32 v22, v8
	v_mov_b32_e32 v23, v4
	v_pk_fma_f32 v[16:17], v[22:23], v[22:23], v[16:17]
	v_mov_b32_e32 v22, v9
	v_mov_b32_e32 v23, v5
	v_pk_fma_f32 v[76:77], v[22:23], v[22:23], v[16:17]
	global_load_dwordx4 v[22:25], v[14:15], off offset:2048
	s_nop 0
	global_load_dwordx4 v[14:17], v[14:15], off offset:3072
	s_waitcnt vmcnt(1)
	v_mov_b32_e32 v32, v23
	s_waitcnt vmcnt(0)
	v_mov_b32_e32 v33, v15
	v_mov_b32_e32 v30, v22
	v_mov_b32_e32 v31, v14
	v_pk_mul_f32 v[32:33], v[32:33], v[32:33]
	s_nop 0
	v_pk_fma_f32 v[30:31], v[30:31], v[30:31], v[32:33]
	v_mov_b32_e32 v32, v24
	v_mov_b32_e32 v33, v16
	v_pk_fma_f32 v[30:31], v[32:33], v[32:33], v[30:31]
	v_mov_b32_e32 v32, v25
	v_mov_b32_e32 v33, v17
	v_pk_fma_f32 v[80:81], v[32:33], v[32:33], v[30:31]
	v_lshlrev_b64 v[30:31], 12, v[72:73]
	v_lshl_add_u64 v[58:59], v[68:69], 0, v[30:31]
	global_load_dwordx4 v[38:41], v[58:59], off
	global_load_dwordx4 v[30:33], v[58:59], off offset:1024
	s_waitcnt vmcnt(1)
	v_mov_b32_e32 v62, v39
	s_waitcnt vmcnt(0)
	v_mov_b32_e32 v63, v31
	v_mov_b32_e32 v60, v38
	v_mov_b32_e32 v61, v30
	v_pk_mul_f32 v[62:63], v[62:63], v[62:63]
	s_nop 0
	v_pk_fma_f32 v[60:61], v[60:61], v[60:61], v[62:63]
	v_mov_b32_e32 v62, v40
	v_mov_b32_e32 v63, v32
	v_pk_fma_f32 v[60:61], v[62:63], v[62:63], v[60:61]
	v_mov_b32_e32 v62, v41
	v_mov_b32_e32 v63, v33
	v_pk_fma_f32 v[68:69], v[62:63], v[62:63], v[60:61]
	global_load_dwordx4 v[62:65], v[58:59], off offset:2048
	s_nop 0
	global_load_dwordx4 v[58:61], v[58:59], off offset:3072
	s_waitcnt vmcnt(1)
	v_mov_b32_e32 v94, v63
	s_waitcnt vmcnt(0)
	v_mov_b32_e32 v95, v59
	v_mov_b32_e32 v92, v62
	v_mov_b32_e32 v93, v58
	v_pk_mul_f32 v[94:95], v[94:95], v[94:95]
	s_nop 0
	v_pk_fma_f32 v[92:93], v[92:93], v[92:93], v[94:95]
	v_mov_b32_e32 v94, v64
	v_mov_b32_e32 v95, v60
	v_pk_fma_f32 v[92:93], v[94:95], v[94:95], v[92:93]
	v_mov_b32_e32 v94, v65
	v_mov_b32_e32 v95, v61
	v_pk_fma_f32 v[92:93], v[94:95], v[94:95], v[92:93]
	v_mov_b32_e32 v94, v86
	v_mov_b32_e32 v95, v78
	v_mov_b32_e32 v78, v87
	v_pk_add_f32 v[78:79], v[94:95], v[78:79]
	v_mov_b32_e32 v86, v88
	v_mov_b32_e32 v87, v84
	v_pk_add_f32 v[78:79], v[78:79], v[86:87]
	v_mov_b32_e32 v84, v89
	v_pk_add_f32 v[78:79], v[78:79], v[84:85]
	ds_bpermute_b32 v85, v224, v79
	ds_bpermute_b32 v84, v224, v78
	s_waitcnt lgkmcnt(0)
	v_pk_add_f32 v[78:79], v[78:79], v[84:85]
	ds_bpermute_b32 v85, v228, v79
	ds_bpermute_b32 v84, v228, v78
	s_waitcnt lgkmcnt(0)
	v_pk_add_f32 v[78:79], v[78:79], v[84:85]
	ds_bpermute_b32 v85, v227, v79
	ds_bpermute_b32 v84, v227, v78
	s_waitcnt lgkmcnt(0)
	v_pk_add_f32 v[78:79], v[78:79], v[84:85]
	ds_bpermute_b32 v85, v226, v79
	ds_bpermute_b32 v84, v226, v78
	s_waitcnt lgkmcnt(0)
	v_pk_add_f32 v[78:79], v[78:79], v[84:85]
	ds_bpermute_b32 v85, v225, v79
	ds_bpermute_b32 v84, v225, v78
	s_waitcnt lgkmcnt(0)
	v_pk_add_f32 v[78:79], v[78:79], v[84:85]
	ds_bpermute_b32 v85, v223, v79
	ds_bpermute_b32 v84, v223, v78
	s_waitcnt lgkmcnt(0)
	v_pk_add_f32 v[78:79], v[78:79], v[84:85]
	s_nop 0
	v_pk_fma_f32 v[78:79], v[78:79], s[4:5], v[70:71] op_sel_hi:[1,0,0]
	s_nop 0
	v_mul_f32_e32 v0, 0x4b800000, v79
	v_cmp_gt_f32_e64 s[0:1], s3, v79
	v_cmp_gt_f32_e32 vcc, s3, v78
	s_nop 0
	v_cndmask_b32_e64 v0, v79, v0, s[0:1]
	v_rsq_f32_e32 v0, v0
	s_nop 0
	v_mul_f32_e32 v79, 0x45800000, v0
	v_cndmask_b32_e64 v0, v0, v79, s[0:1]
	v_pk_mul_f32 v[10:11], v[10:11], v[0:1] op_sel_hi:[1,0]
	v_pk_mul_f32 v[12:13], v[12:13], v[0:1] op_sel_hi:[1,0]
	v_cvt_pk_f16_f32 v10, v10, v11
	v_cvt_pk_f16_f32 v11, v12, v13
	global_store_dwordx2 v[90:91], v[10:11], off offset:512
	v_pk_mul_f32 v[10:11], v[34:35], v[0:1] op_sel_hi:[1,0]
	v_pk_mul_f32 v[12:13], v[36:37], v[0:1] op_sel_hi:[1,0]
	v_cvt_pk_f16_f32 v10, v10, v11
	v_cvt_pk_f16_f32 v11, v12, v13
	v_pk_mul_f32 v[18:19], v[18:19], v[0:1] op_sel_hi:[1,0]
	v_pk_mul_f32 v[20:21], v[20:21], v[0:1] op_sel_hi:[1,0]
	global_store_dwordx2 v[90:91], v[10:11], off offset:1024
	v_pk_mul_f32 v[10:11], v[26:27], v[0:1] op_sel_hi:[1,0]
	v_pk_mul_f32 v[12:13], v[28:29], v[0:1] op_sel_hi:[1,0]
	v_mul_f32_e32 v0, 0x4b800000, v78
	v_cndmask_b32_e32 v0, v78, v0, vcc
	v_rsq_f32_e32 v0, v0
	v_cvt_pk_f16_f32 v10, v10, v11
	v_cvt_pk_f16_f32 v11, v12, v13
	global_store_dwordx2 v[90:91], v[10:11], off offset:1536
	v_mul_f32_e32 v10, 0x45800000, v0
	v_cvt_pk_f16_f32 v18, v18, v19
	v_cvt_pk_f16_f32 v19, v20, v21
	v_cndmask_b32_e32 v0, v0, v10, vcc
	global_store_dwordx2 v[90:91], v[18:19], off
	v_lshlrev_b64 v[10:11], 11, v[74:75]
	v_pk_mul_f32 v[12:13], v[46:47], v[0:1] op_sel_hi:[1,0]
	v_pk_mul_f32 v[18:19], v[48:49], v[0:1] op_sel_hi:[1,0]
	v_lshl_add_u64 v[10:11], v[66:67], 0, v[10:11]
	v_cvt_pk_f16_f32 v12, v12, v13
	v_cvt_pk_f16_f32 v13, v18, v19
	global_store_dwordx2 v[10:11], v[12:13], off
	v_pk_mul_f32 v[12:13], v[42:43], v[0:1] op_sel_hi:[1,0]
	v_pk_mul_f32 v[18:19], v[44:45], v[0:1] op_sel_hi:[1,0]
	v_cvt_pk_f16_f32 v12, v12, v13
	v_cvt_pk_f16_f32 v13, v18, v19
	global_store_dwordx2 v[10:11], v[12:13], off offset:512
	v_pk_mul_f32 v[12:13], v[54:55], v[0:1] op_sel_hi:[1,0]
	v_pk_mul_f32 v[18:19], v[56:57], v[0:1] op_sel_hi:[1,0]
	v_cvt_pk_f16_f32 v12, v12, v13
	v_cvt_pk_f16_f32 v13, v18, v19
	global_store_dwordx2 v[10:11], v[12:13], off offset:1024
	v_pk_mul_f32 v[12:13], v[50:51], v[0:1] op_sel_hi:[1,0]
	v_pk_mul_f32 v[18:19], v[52:53], v[0:1] op_sel_hi:[1,0]
	v_cvt_pk_f16_f32 v12, v12, v13
	v_cvt_pk_f16_f32 v13, v18, v19
	global_store_dwordx2 v[10:11], v[12:13], off offset:1536
	v_mov_b32_e32 v12, v68
	v_mov_b32_e32 v13, v76
	v_mov_b32_e32 v76, v69
	v_pk_add_f32 v[12:13], v[12:13], v[76:77]
	v_mov_b32_e32 v18, v92
	v_mov_b32_e32 v19, v80
	v_pk_add_f32 v[12:13], v[12:13], v[18:19]
	v_mov_b32_e32 v80, v93
	v_pk_add_f32 v[12:13], v[12:13], v[80:81]
	ds_bpermute_b32 v19, v224, v13
	ds_bpermute_b32 v18, v224, v12
	v_lshlrev_b64 v[10:11], 11, v[82:83]
	v_lshl_add_u64 v[10:11], v[66:67], 0, v[10:11]
	s_waitcnt lgkmcnt(0)
; DI int otid() { int t = threadIdx.x; asm volatile("" : "+v"(t)); return t; }
; template <int MODE, int MT> DI void norm_rows(const float* src, const float* src2, float* x, int d2, bf16_t* xb, const float* __restrict__ g) {
;     ...
; #pragma unroll
;         for (int q = 0; q < 4; ++q) {
;             const int row = wave * (MT * 4) + rb * 4 + q, grow = row + (row >= 64 ? d2 : 0);
;             const float rstd = rsqrtf(ss[q] * (1.f / DM) + 1e-6f);
; #pragma unroll
;             for (int i = 0; i < 4; ++i) {
;                 if (MODE == 0) *(f32x4*)(x + (size_t)grow * DM + i * 256 + lane * 4) = v[q][i];
;                 if (MODE == 2) { f32x4 gg = *(const f32x4*)(g + i * 256 + lane * 4); *(f32x4*)(x + (size_t)grow * DM + i * 256 + lane * 4) = v[q][i] * rstd * gg; }
;                 else { u32x2 o = {pk2(v[q][i][0] * rstd, v[q][i][1] * rstd), pk2(v[q][i][2] * rstd, v[q][i][3] * rstd)}; *(u32x2*)(xb + (size_t)grow * DM + i * 256 + lane * 4) = o; }
;             }
;         }
;     ...
;     constexpr int KS = K / 16, NCH = K / A_CHUNK, PD = 4;
;     const int tid = otid(), wave = tid >> 6, lane = tid & 63, r = lane & 31, h = lane >> 5;
;     const u32x4* Bw = (const u32x4*)Wp;
; #pragma unroll 1
;     for (int pass = 0; pass * NWAVE < NU; ++pass) {
;         const int unit = pass * NWAVE + wave;
;         const bool active = unit < NU;
;         const int ucl = active ? unit : NU - 1;
;         const u32x4* bp = Bw + (size_t)(ucl * NT) * 64 + lane;
;         const size_t kstr = (size_t)NU * NT * 64;
;         f32x16 acc[MT][NT];
; #pragma unroll
;         for (int mi = 0; mi < MT; ++mi)
; #pragma unroll
;             for (int nj = 0; nj < NT; ++nj)
; #pragma unroll
;                 for (int i = 0; i < 16; ++i) acc[mi][nj][i] = 0.f;
;         u32x4 bq[PD][NT];
; #pragma unroll
;         for (int s = 0; s < PD; ++s)
; #pragma unroll
;             for (int j = 0; j < NT; ++j) bq[s][j] = bp[(size_t)s * kstr + j * 64];
;         u32x4 areg[MT];
;         if (pass == 0) __syncthreads();
; #pragma unroll
;         for (int i = 0; i < MT; ++i) { const int idx = i * NTHR + tid, row = idx >> 4, seg = idx & 15; areg[i] = *(const u32x4*)(A + ((row + (i == 2 ? d2 : 0)) * lda + seg * 8)); }
; #pragma unroll
;         for (int i = 0; i < MT; ++i) { const int idx = i * NTHR + tid, row = idx >> 4, seg = idx & 15; *(u32x4*)(lds + row * A_LD + seg * 16) = areg[i]; }
;         lds_barrier();
	v_pk_add_f32 v[12:13], v[12:13], v[18:19]
	ds_bpermute_b32 v19, v228, v13
	ds_bpermute_b32 v18, v228, v12
	s_waitcnt lgkmcnt(0)
	v_pk_add_f32 v[12:13], v[12:13], v[18:19]
	ds_bpermute_b32 v19, v227, v13
	ds_bpermute_b32 v18, v227, v12
	s_waitcnt lgkmcnt(0)
	v_pk_add_f32 v[12:13], v[12:13], v[18:19]
	ds_bpermute_b32 v19, v226, v13
	ds_bpermute_b32 v18, v226, v12
	s_waitcnt lgkmcnt(0)
	v_pk_add_f32 v[12:13], v[12:13], v[18:19]
	ds_bpermute_b32 v19, v225, v13
	ds_bpermute_b32 v18, v225, v12
	s_waitcnt lgkmcnt(0)
	v_pk_add_f32 v[12:13], v[12:13], v[18:19]
	ds_bpermute_b32 v19, v223, v13
	ds_bpermute_b32 v18, v223, v12
	s_waitcnt lgkmcnt(0)
	v_pk_add_f32 v[12:13], v[12:13], v[18:19]
	s_nop 0
	v_pk_fma_f32 v[12:13], v[12:13], s[4:5], v[70:71] op_sel_hi:[1,0,0]
	s_nop 0
	v_mul_f32_e32 v0, 0x4b800000, v13
	v_cmp_gt_f32_e64 s[0:1], s3, v13
	v_cmp_gt_f32_e32 vcc, s3, v12
	v_readlane_b32 s3, v252, 45
	v_cndmask_b32_e64 v0, v13, v0, s[0:1]
	v_rsq_f32_e32 v0, v0
	s_nop 0
	v_mul_f32_e32 v13, 0x45800000, v0
	v_cndmask_b32_e64 v0, v0, v13, s[0:1]
	v_pk_mul_f32 v[2:3], v[2:3], v[0:1] op_sel_hi:[1,0]
	v_pk_mul_f32 v[4:5], v[4:5], v[0:1] op_sel_hi:[1,0]
	v_cvt_pk_f16_f32 v2, v2, v3
	v_cvt_pk_f16_f32 v3, v4, v5
	global_store_dwordx2 v[10:11], v[2:3], off offset:512
	v_pk_mul_f32 v[2:3], v[22:23], v[0:1] op_sel_hi:[1,0]
	v_pk_mul_f32 v[4:5], v[24:25], v[0:1] op_sel_hi:[1,0]
	v_cvt_pk_f16_f32 v2, v2, v3
	v_cvt_pk_f16_f32 v3, v4, v5
	v_pk_mul_f32 v[6:7], v[6:7], v[0:1] op_sel_hi:[1,0]
	v_pk_mul_f32 v[8:9], v[8:9], v[0:1] op_sel_hi:[1,0]
	global_store_dwordx2 v[10:11], v[2:3], off offset:1024
	v_pk_mul_f32 v[2:3], v[14:15], v[0:1] op_sel_hi:[1,0]
	v_pk_mul_f32 v[4:5], v[16:17], v[0:1] op_sel_hi:[1,0]
	v_mul_f32_e32 v0, 0x4b800000, v12
	v_cndmask_b32_e32 v0, v12, v0, vcc
	v_rsq_f32_e32 v0, v0
	v_cvt_pk_f16_f32 v2, v2, v3
	v_cvt_pk_f16_f32 v3, v4, v5
	global_store_dwordx2 v[10:11], v[2:3], off offset:1536
	v_mul_f32_e32 v2, 0x45800000, v0
	v_cvt_pk_f16_f32 v6, v6, v7
	v_cvt_pk_f16_f32 v7, v8, v9
	v_cndmask_b32_e32 v0, v0, v2, vcc
	global_store_dwordx2 v[10:11], v[6:7], off
	v_lshlrev_b64 v[2:3], 11, v[72:73]
	v_pk_mul_f32 v[4:5], v[38:39], v[0:1] op_sel_hi:[1,0]
	v_pk_mul_f32 v[6:7], v[40:41], v[0:1] op_sel_hi:[1,0]
	v_lshl_add_u64 v[2:3], v[66:67], 0, v[2:3]
	v_cvt_pk_f16_f32 v4, v4, v5
	v_cvt_pk_f16_f32 v5, v6, v7
	global_store_dwordx2 v[2:3], v[4:5], off
	v_pk_mul_f32 v[4:5], v[30:31], v[0:1] op_sel_hi:[1,0]
	v_pk_mul_f32 v[6:7], v[32:33], v[0:1] op_sel_hi:[1,0]
	v_cvt_pk_f16_f32 v4, v4, v5
	v_cvt_pk_f16_f32 v5, v6, v7
	global_store_dwordx2 v[2:3], v[4:5], off offset:512
	v_pk_mul_f32 v[4:5], v[62:63], v[0:1] op_sel_hi:[1,0]
	v_pk_mul_f32 v[6:7], v[64:65], v[0:1] op_sel_hi:[1,0]
	v_cvt_pk_f16_f32 v4, v4, v5
	v_cvt_pk_f16_f32 v5, v6, v7
	s_mul_i32 s1, s73, 0xb000
	global_store_dwordx2 v[2:3], v[4:5], off offset:1024
	v_pk_mul_f32 v[4:5], v[58:59], v[0:1] op_sel_hi:[1,0]
	v_pk_mul_f32 v[6:7], v[60:61], v[0:1] op_sel_hi:[1,0]
	s_mul_hi_i32 s0, s73, 0xb000
	s_add_u32 s8, s3, s1
	v_readlane_b32 s1, v252, 46
	v_cvt_pk_f16_f32 v4, v4, v5
	v_cvt_pk_f16_f32 v5, v6, v7
	s_addc_u32 s9, s1, s0
	s_mul_hi_i32 s0, s74, 0xb000
	s_mul_i32 s74, s74, 0xb000
	v_readlane_b32 s1, v255, 46
	v_mov_b32_e32 v0, v176
	global_store_dwordx2 v[2:3], v[4:5], off offset:1536
	s_add_u32 s28, s1, s74
	v_readlane_b32 s1, v255, 47
	s_addc_u32 s29, s1, s0
	v_lshlrev_b32_e32 v5, 3, v0
	v_and_b32_e32 v2, 63, v0
	v_readlane_b32 s0, v255, 44
	v_and_b32_e32 v10, 0x78, v5
	v_lshlrev_b32_e32 v5, 4, v0
	v_lshlrev_b32_e32 v2, 4, v2
	v_mov_b32_e32 v3, v1
	v_readlane_b32 s1, v255, 45
	v_and_b32_e32 v224, 0xf0, v5
	v_lshrrev_b32_e32 v5, 1, v0
	v_and_b32_e32 v4, 31, v0
	v_lshl_add_u64 v[156:157], s[0:1], 0, v[2:3]
	v_and_b32_e32 v5, 16, v5
	s_movk_i32 s0, 0x110
	v_ashrrev_i32_e32 v11, 4, v0
	v_mad_u32_u24 v225, v4, s0, v5
	v_lshl_or_b32 v4, v11, 10, v10
	v_ashrrev_i32_e32 v5, 31, v4
	v_lshl_add_u64 v[158:159], v[4:5], 1, s[34:35]
	v_add_u32_e32 v5, 0x200, v0
	v_ashrrev_i32_e32 v5, 4, v5
	v_ashrrev_i32_e32 v223, 6, v0
	v_lshl_or_b32 v6, v5, 10, v10
	v_add_u32_e32 v0, 0x400, v0
	v_ashrrev_i32_e32 v7, 31, v6
	v_ashrrev_i32_e32 v0, 4, v0
	v_lshl_add_u64 v[160:161], v[6:7], 1, s[34:35]
	v_add_u32_e32 v7, s24, v0
	v_mul_lo_u32 v226, v11, s0
	v_mul_lo_u32 v227, v5, s0
	v_mul_lo_u32 v228, v0, s0
	v_readlane_b32 s0, v255, 23
	v_lshl_or_b32 v8, v7, 10, v10
	v_readlane_b32 s1, v255, 24
	v_ashrrev_i32_e32 v9, 31, v8
	v_add_lshl_u32 v0, v0, s55, 10
	v_lshl_add_u64 v[164:165], s[0:1], 0, v[2:3]
	s_movk_i32 s0, 0x80
	v_lshl_add_u64 v[162:163], v[8:9], 1, s[34:35]
	v_or_b32_e32 v229, 0x80, v4
	v_or3_b32 v230, v0, v10, s0
	v_or_b32_e32 v231, 0x80, v6
	v_mov_b32_e32 v232, v223
	s_waitcnt vmcnt(0)
	s_barrier
	v_readlane_b32 s10, v252, 10
	v_readlane_b32 s11, v252, 11
	v_readlane_b32 s0, v255, 42
	s_nop 3
	s_lshl_b32 s0, s0, 2
	s_add_u32 s0, s0, s73
	s_lshl_b32 s0, s0, 3
	s_add_u32 s10, s10, s0
	s_addc_u32 s11, s11, 0
	v_readfirstlane_b32 s0, v223
	s_nop 3
	s_cmp_lg_u32 s0, 0
	s_cbranch_scc1 .Lm3u_claim
	s_mov_b64 s[2:3], exec
	s_mov_b64 exec, 1
	buffer_wbl2 sc1
	s_waitcnt vmcnt(0)
	s_getreg_b32 s0, hwreg(HW_REG_XCC_ID, 0, 4)
	s_add_u32 s0, s0, 1
	v_mov_b32_e32 v2, s0
	global_atomic_or v1, v2, s[10:11] offset:260
	s_mov_b64 exec, s[2:3]
	s_branch .Lm3u_claim

; DI const bf16_t* wp(const Params& p, int l, size_t off) { return (const bf16_t*)(p.ws + OFF_WP) + (size_t)l * PW_LAYER + off; }
; template <int MT> DI void phaseB(const Params& p, int l, int t, unsigned char* lds) {
;     ...
;     EpiUp<MT> eu; eu.priv = priv; eu.d2 = d2;
;     eu.halo = (float*)(ws + OFF_UHALO) + (size_t)t * 2 * DFF2;
;     eu.pconv = t == NTILE - 1 ? p.out + O_PCONV + (size_t)l * 2 * DFF2 : nullptr;
;     eu.sconv = p.out + O_SCONV + ((size_t)l * 8 + 2 * t) * 2 * DFF2;
;     gemm64<1024, MT>(xb, DM, d2, wp(p, l, PW_UP), DFF2 / UW, lds, eu);
.LBB0_705:
	v_readlane_b32 s0, v254, 57
	s_nop 3
	s_cmp_lt_u32 s0, 4
	s_cbranch_scc1 .Lhu_done
	s_and_b32 s0, s0, 31
	s_cmp_gt_u32 s0, 4
	s_cbranch_scc1 .Lhu_done
	v_writelane_b32 v180, s0, 0
	v_writelane_b32 v180, s1, 1
	v_writelane_b32 v180, s2, 2
	v_writelane_b32 v180, s3, 3
	v_writelane_b32 v180, s4, 4
	v_writelane_b32 v180, s5, 5
	v_writelane_b32 v180, s6, 6
	v_writelane_b32 v180, s7, 7
	v_writelane_b32 v180, s8, 8
	v_writelane_b32 v180, s9, 9
	v_writelane_b32 v180, s10, 10
	v_writelane_b32 v180, s11, 11
	v_writelane_b32 v180, s12, 12
	v_writelane_b32 v180, s13, 13
	v_writelane_b32 v180, s14, 14
	v_writelane_b32 v180, s15, 15
	v_writelane_b32 v180, s16, 16
	v_writelane_b32 v180, s17, 17
	v_writelane_b32 v180, s18, 18
	v_writelane_b32 v180, s19, 19
	v_writelane_b32 v180, s20, 20
	v_writelane_b32 v180, s21, 21
	v_writelane_b32 v180, s22, 22
	v_writelane_b32 v180, s23, 23
	v_writelane_b32 v180, s24, 24
	v_writelane_b32 v180, s25, 25
	v_writelane_b32 v180, s26, 26
	v_writelane_b32 v180, s27, 27
	v_writelane_b32 v180, s28, 28
	v_writelane_b32 v180, s29, 29
	v_writelane_b32 v180, s30, 30
	v_writelane_b32 v180, s31, 31
	v_writelane_b32 v180, s32, 32
	v_writelane_b32 v180, s33, 33
	v_writelane_b32 v180, s34, 34
	v_writelane_b32 v180, s35, 35
	v_writelane_b32 v180, s36, 36
	v_writelane_b32 v180, s37, 37
	v_writelane_b32 v180, s38, 38
	v_writelane_b32 v180, s39, 39
	v_writelane_b32 v180, s40, 40
	v_writelane_b32 v180, s41, 41
	v_writelane_b32 v180, s42, 42
	v_writelane_b32 v180, s43, 43
	v_writelane_b32 v180, s44, 44
	v_writelane_b32 v180, s45, 45
	v_writelane_b32 v180, s46, 46
	v_writelane_b32 v180, s47, 47
	v_writelane_b32 v180, s48, 48
	v_writelane_b32 v180, s49, 49
	v_writelane_b32 v180, s50, 50
	v_writelane_b32 v180, s51, 51
	v_writelane_b32 v180, s52, 52
	v_writelane_b32 v180, s53, 53
	v_writelane_b32 v180, s54, 54
	v_writelane_b32 v180, s55, 55
	v_writelane_b32 v180, s56, 56
	v_writelane_b32 v180, s57, 57
	v_writelane_b32 v180, s58, 58
	v_writelane_b32 v180, s59, 59
	v_writelane_b32 v180, s60, 60
	v_writelane_b32 v180, s61, 61
	v_writelane_b32 v180, s62, 62
	v_writelane_b32 v180, s63, 63
	v_writelane_b32 v181, s64, 0
	v_writelane_b32 v181, s65, 1
	v_writelane_b32 v181, s66, 2
	v_writelane_b32 v181, s67, 3
	v_writelane_b32 v181, s68, 4
	v_writelane_b32 v181, s69, 5
	v_writelane_b32 v181, s70, 6
	v_writelane_b32 v181, s71, 7
	v_writelane_b32 v181, s72, 8
	v_writelane_b32 v181, s73, 9
	v_writelane_b32 v181, s74, 10
	v_writelane_b32 v181, s75, 11
	v_writelane_b32 v181, s76, 12
	v_writelane_b32 v181, s77, 13
	v_writelane_b32 v181, s78, 14
	v_writelane_b32 v181, s79, 15
	v_writelane_b32 v181, s80, 16
	v_writelane_b32 v181, s81, 17
	v_writelane_b32 v181, s82, 18
	v_writelane_b32 v181, s83, 19
	v_writelane_b32 v181, s84, 20
	v_writelane_b32 v181, s85, 21
	v_writelane_b32 v181, s86, 22
	v_writelane_b32 v181, s87, 23
	v_writelane_b32 v181, s88, 24
	v_writelane_b32 v181, s89, 25
	v_writelane_b32 v181, s90, 26
	v_writelane_b32 v181, s91, 27
	v_writelane_b32 v181, s92, 28
	v_writelane_b32 v181, s93, 29
	v_writelane_b32 v181, s94, 30
	v_writelane_b32 v181, s95, 31
	v_writelane_b32 v181, s96, 32
	v_writelane_b32 v181, s97, 33
	v_writelane_b32 v181, s98, 34
	v_writelane_b32 v181, s99, 35
	v_writelane_b32 v181, s100, 36
	v_writelane_b32 v181, s101, 37
	v_writelane_b32 v181, vcc_lo, 38
	v_writelane_b32 v181, vcc_hi, 39
	s_getreg_b32 s70, hwreg(HW_REG_XCC_ID, 0, 4)
	s_mov_b32 s43, 0xb0000
	s_movk_i32 s44, 0x1600
	s_mov_b32 s65, 0
	v_readlane_b32 s66, v252, 10
	v_readlane_b32 s67, v252, 11
	v_readlane_b32 s68, v254, 57
	s_mov_b32 s69, 0
	s_mov_b32 s80, 0
	v_lshrrev_b32_e32 v223, 6, v176

; DI const bf16_t* wp(const Params& p, int l, size_t off) { return (const bf16_t*)(p.ws + OFF_WP) + (size_t)l * PW_LAYER + off; }
; template <int MT> DI void phaseB(const Params& p, int l, int t, unsigned char* lds) {
;     ...
;     EpiUp<MT> eu; eu.priv = priv; eu.d2 = d2;
;     eu.halo = (float*)(ws + OFF_UHALO) + (size_t)t * 2 * DFF2;
;     eu.pconv = t == NTILE - 1 ? p.out + O_PCONV + (size_t)l * 2 * DFF2 : nullptr;
;     eu.sconv = p.out + O_SCONV + ((size_t)l * 8 + 2 * t) * 2 * DFF2;
;     gemm64<1024, MT>(xb, DM, d2, wp(p, l, PW_UP), DFF2 / UW, lds, eu);
.Lhu_poll:
	global_load_dword v2, v1, s[74:75] offset:260 sc1
	s_waitcnt vmcnt(0)
	v_readfirstlane_b32 s0, v2
	s_nop 3
	s_cmp_lg_u32 s0, 0
	s_cbranch_scc1 .Lhu_got
	s_sleep 40
	s_add_u32 s77, s77, 1
	s_cmp_lt_u32 s77, 500
	s_cbranch_scc1 .Lhu_poll

; DI int otid() { int t = threadIdx.x; asm volatile("" : "+v"(t)); return t; }
; DI const bf16_t* wp(const Params& p, int l, size_t off) { return (const bf16_t*)(p.ws + OFF_WP) + (size_t)l * PW_LAYER + off; }
;     ...
;     constexpr int KS = K / 16, NCH = K / A_CHUNK, PD = 4;
;     const int tid = otid(), wave = tid >> 6, lane = tid & 63, r = lane & 31, h = lane >> 5;
;     const u32x4* Bw = (const u32x4*)Wp;
; #pragma unroll 1
;     for (int pass = 0; pass * NWAVE < NU; ++pass) {
;         const int unit = pass * NWAVE + wave;
;         const bool active = unit < NU;
;         const int ucl = active ? unit : NU - 1;
;         const u32x4* bp = Bw + (size_t)(ucl * NT) * 64 + lane;
; template <int MT> DI void phaseB(const Params& p, int l, int t, unsigned char* lds) {
;     ...
;     EpiUp<MT> eu; eu.priv = priv; eu.d2 = d2;
;     eu.halo = (float*)(ws + OFF_UHALO) + (size_t)t * 2 * DFF2;
;     eu.pconv = t == NTILE - 1 ? p.out + O_PCONV + (size_t)l * 2 * DFF2 : nullptr;
;     eu.sconv = p.out + O_SCONV + ((size_t)l * 8 + 2 * t) * 2 * DFF2;
;     gemm64<1024, MT>(xb, DM, d2, wp(p, l, PW_UP), DFF2 / UW, lds, eu);
.Lhu_polled:
	s_barrier
	ds_read_b32 v2, v3
	s_waitcnt lgkmcnt(0)
	v_readfirstlane_b32 s0, v2
	s_nop 3
	s_cmp_eq_u32 s0, 0
	s_cbranch_scc1 .Lhu_next
	buffer_inv sc1
	s_waitcnt vmcnt(0)
	v_readlane_b32 s0, v252, 4
	v_readlane_b32 s1, v252, 5
	s_lshl_b32 s2, s71, 17
	s_add_u32 s34, s0, 0x7c00000
	s_addc_u32 s35, s1, 0
	s_add_u32 s34, s34, s2
	s_addc_u32 s35, s35, 0
	s_mul_i32 s2, s71, 0xb0000
	s_add_u32 s6, s0, 0x9c40000
	s_addc_u32 s7, s1, 0
	s_add_u32 s6, s6, s2
	s_addc_u32 s7, s7, 0
	s_mul_i32 s2, s71, 0xb000
	s_add_u32 s8, s0, 0x175f0000
	s_addc_u32 s9, s1, 0
	s_add_u32 s8, s8, s2
	s_addc_u32 s9, s9, 0
	v_readlane_b32 s10, v252, 2
	v_readlane_b32 s11, v252, 3
	s_mul_i32 s2, s60, 0x58000
	s_mul_i32 s3, s71, 0x16000
	s_add_u32 s2, s2, s3
	s_add_u32 s2, s2, 0x4fac000
	s_add_u32 s28, s10, s2
	s_addc_u32 s29, s11, 0
	s_mul_i32 s2, s60, 0x1f00000
	s_add_u32 s14, s0, s2
	s_addc_u32 s15, s1, 0
	s_add_u32 s12, s14, 0xe80000
	s_addc_u32 s13, s15, 0
	s_lshl_b32 s2, s71, 5
	s_sub_u32 s24, 0x3fc0, s2
	s_mov_b32 s55, s24
	s_sub_u32 s59, 0x4000, s2
	v_mov_b32_e32 v0, v176
	v_lshlrev_b32_e32 v5, 3, v0
	v_and_b32_e32 v2, 63, v0
	s_mov_b32 s0, s12
	v_and_b32_e32 v10, 0x78, v5
	v_lshlrev_b32_e32 v5, 4, v0
	v_lshlrev_b32_e32 v2, 4, v2
	v_mov_b32_e32 v3, v1
	s_mov_b32 s1, s13
	v_and_b32_e32 v224, 0xf0, v5
	v_lshrrev_b32_e32 v5, 1, v0
	v_and_b32_e32 v4, 31, v0
	v_lshl_add_u64 v[156:157], s[0:1], 0, v[2:3]
	v_and_b32_e32 v5, 16, v5
	s_movk_i32 s0, 0x110
	v_ashrrev_i32_e32 v11, 4, v0
	v_mad_u32_u24 v225, v4, s0, v5
	v_lshl_or_b32 v4, v11, 10, v10
	v_ashrrev_i32_e32 v5, 31, v4
	v_lshl_add_u64 v[158:159], v[4:5], 1, s[34:35]
	v_add_u32_e32 v5, 0x200, v0
	v_ashrrev_i32_e32 v5, 4, v5
	v_ashrrev_i32_e32 v223, 6, v0
	v_lshl_or_b32 v6, v5, 10, v10
	v_add_u32_e32 v0, 0x400, v0
	v_ashrrev_i32_e32 v7, 31, v6
	v_ashrrev_i32_e32 v0, 4, v0
	v_lshl_add_u64 v[160:161], v[6:7], 1, s[34:35]
	v_add_u32_e32 v7, s24, v0
	v_mul_lo_u32 v226, v11, s0
	v_mul_lo_u32 v227, v5, s0
	v_mul_lo_u32 v228, v0, s0
	s_mov_b32 s0, s14
	v_lshl_or_b32 v8, v7, 10, v10
	s_mov_b32 s1, s15
	v_ashrrev_i32_e32 v9, 31, v8
	v_add_lshl_u32 v0, v0, s55, 10
	v_lshl_add_u64 v[164:165], s[0:1], 0, v[2:3]
	s_movk_i32 s0, 0x80
	v_lshl_add_u64 v[162:163], v[8:9], 1, s[34:35]
	v_or_b32_e32 v229, 0x80, v4
	v_or3_b32 v230, v0, v10, s0
	v_or_b32_e32 v231, 0x80, v6
	v_mov_b32_e32 v232, v223
